# attention loop: only the next-tile prefetch address block runs at low priority; staging writes, QK, softmax and PV stay raised
# speedup vs baseline: 1.0043x; 1.0002x over previous
.LBB0_393:
	s_add_i32 s64, s65, 1
	s_waitcnt vmcnt(7)
	ds_write_b128 v220, v[80:83]
	s_waitcnt vmcnt(6)
	ds_write_b128 v221, v[84:87] offset:4608
	s_waitcnt vmcnt(5)
	ds_write_b128 v220, v[88:91] offset:1152
	s_waitcnt vmcnt(4)
	ds_write_b128 v221, v[92:95] offset:5888
	s_waitcnt vmcnt(3)
	ds_write_b128 v220, v[96:99] offset:2304
	s_waitcnt vmcnt(2)
	ds_write_b128 v221, v[100:103] offset:7168
	s_waitcnt vmcnt(1)
	ds_write_b128 v220, v[104:107] offset:3456
	v_cmp_lt_u32_e32 vcc, s64, v150
	s_waitcnt vmcnt(0)
	ds_write_b128 v221, v[108:111] offset:8448
	ds_read_b128 v[158:161], v147
	ds_read_b128 v[162:165], v147 offset:32
	ds_read_b128 v[166:169], v147 offset:64
	ds_read_b128 v[170:173], v147 offset:96
	s_setprio 0
	s_and_saveexec_b64 s[8:9], vcc
	s_cbranch_execz .LBB0_401
	v_mov_b32_e32 v38, v131
	v_mov_b64_e32 v[32:33], 0x100
	v_mov_b32_e32 v112, s63
	v_mov_b64_e32 v[36:37], v[128:129]
	v_mov_b64_e32 v[34:35], v[138:139]
	s_and_saveexec_b64 s[44:45], s[6:7]
	s_cbranch_execz .LBB0_400
	s_cmp_gt_u32 s65, 14
	s_mov_b64 s[46:47], -1
	s_cbranch_scc0 .LBB0_397
	s_add_i32 s36, s65, -15
	s_lshr_b32 s36, s36, 1
	v_add_u32_e32 v36, s36, v119
	s_and_b32 s66, s63, 32
	v_lshl_or_b32 v112, v36, 6, s66
	v_lshlrev_b64 v[32:33], 10, v[112:113]
	v_lshlrev_b32_e32 v112, 7, v36
	v_lshl_add_u64 v[34:35], v[134:135], 0, v[32:33]
	v_lshl_add_u64 v[36:37], v[136:137], 0, v[112:113]
	s_mov_b64 s[46:47], 0

.LBB0_401:
	s_or_b64 exec, exec, s[8:9]
	s_setprio 1
	s_cmp_gt_u32 s65, 15
	s_cselect_b64 s[8:9], -1, 0
	s_and_b64 s[8:9], s[42:43], s[8:9]
	s_waitcnt lgkmcnt(3)
	v_mfma_f32_32x32x16_bf16 v[32:47], v[158:161], v[64:67], 0
	s_waitcnt lgkmcnt(2)
	v_mfma_f32_32x32x16_bf16 v[32:47], v[162:165], v[68:71], v[32:47]
	s_waitcnt lgkmcnt(1)
	v_mfma_f32_32x32x16_bf16 v[32:47], v[166:169], v[72:75], v[32:47]
	s_waitcnt lgkmcnt(0)
	v_mfma_f32_32x32x16_bf16 v[32:47], v[170:173], v[76:79], v[32:47]
	s_and_saveexec_b64 s[44:45], s[8:9]
	s_cbranch_execz .LBB0_392
	s_add_i32 s9, s65, -16
	s_ashr_i32 s9, s9, 1
	s_sub_i32 s8, s63, 32
	v_add_u32_e32 v48, s9, v152
	v_and_or_b32 v112, s8, 32, v145
	v_mad_u64_u32 v[140:141], s[8:9], v48, 31, v[120:121]
	v_subrev_u32_e32 v207, s14, v132
	v_add_u32_e32 v140, 15, v140
	v_mov_b32_e32 v210, 0xf149f2ca
	v_lshl_add_u32 v207, v140, 2, v207
	v_sub_u32_e32 v188, v112, v151
	v_sub_u32_e32 v189, v112, v153
	v_add_u32_e32 v209, 0, v188
	v_med3_i32 v209, v209, -15, 15
	v_lshl_add_u32 v209, v209, 2, v207
	global_load_dword v190, v209, s[14:15]
	v_add_u32_e32 v209, 1, v188
	v_med3_i32 v209, v209, -15, 15
	v_lshl_add_u32 v209, v209, 2, v207
	global_load_dword v191, v209, s[14:15]
	v_add_u32_e32 v209, 2, v188
	v_med3_i32 v209, v209, -15, 15
	v_lshl_add_u32 v209, v209, 2, v207
	global_load_dword v192, v209, s[14:15]
	v_add_u32_e32 v209, 3, v188
	v_med3_i32 v209, v209, -15, 15
	v_lshl_add_u32 v209, v209, 2, v207
	global_load_dword v193, v209, s[14:15]
	v_add_u32_e32 v209, 8, v188
	v_med3_i32 v209, v209, -15, 15
	v_lshl_add_u32 v209, v209, 2, v207
	global_load_dword v194, v209, s[14:15]
	v_add_u32_e32 v209, 9, v188
	v_med3_i32 v209, v209, -15, 15
	v_lshl_add_u32 v209, v209, 2, v207
	global_load_dword v195, v209, s[14:15]
	v_add_u32_e32 v209, 10, v188
	v_med3_i32 v209, v209, -15, 15
	v_lshl_add_u32 v209, v209, 2, v207
	global_load_dword v196, v209, s[14:15]
	v_add_u32_e32 v209, 11, v188
	v_med3_i32 v209, v209, -15, 15
	v_lshl_add_u32 v209, v209, 2, v207
	global_load_dword v197, v209, s[14:15]
	v_add_u32_e32 v209, 16, v188
	v_med3_i32 v209, v209, -15, 15
	v_lshl_add_u32 v209, v209, 2, v207
	global_load_dword v198, v209, s[14:15]
	v_add_u32_e32 v209, 17, v188
	v_med3_i32 v209, v209, -15, 15
	v_lshl_add_u32 v209, v209, 2, v207
	global_load_dword v199, v209, s[14:15]
	v_add_u32_e32 v209, 18, v188
	v_med3_i32 v209, v209, -15, 15
	v_lshl_add_u32 v209, v209, 2, v207
	global_load_dword v200, v209, s[14:15]
	v_add_u32_e32 v209, 19, v188
	v_med3_i32 v209, v209, -15, 15
	v_lshl_add_u32 v209, v209, 2, v207
	global_load_dword v201, v209, s[14:15]
	v_add_u32_e32 v209, 24, v188
	v_med3_i32 v209, v209, -15, 15
	v_lshl_add_u32 v209, v209, 2, v207
	global_load_dword v202, v209, s[14:15]
	v_add_u32_e32 v209, 25, v188
	v_med3_i32 v209, v209, -15, 15
	v_lshl_add_u32 v209, v209, 2, v207
	global_load_dword v203, v209, s[14:15]
	v_add_u32_e32 v209, 26, v188
	v_med3_i32 v209, v209, -15, 15
	v_lshl_add_u32 v209, v209, 2, v207
	global_load_dword v204, v209, s[14:15]
	v_add_u32_e32 v209, 27, v188
	v_med3_i32 v209, v209, -15, 15
	v_lshl_add_u32 v209, v209, 2, v207
	global_load_dword v205, v209, s[14:15]
	v_add_u32_e32 v208, 0, v189
	v_cmp_gt_u32_e32 vcc, 16, v208
	s_waitcnt vmcnt(0)
	v_fmamk_f32 v32, v190, 0x3fb8aa3b, v32
	v_add_u32_e32 v211, 1, v189
	v_cmp_gt_u32_e64 s[46:47], 16, v211
	v_cndmask_b32_e32 v32, v210, v32, vcc
	v_fmamk_f32 v33, v191, 0x3fb8aa3b, v33
	v_add_u32_e32 v208, 2, v189
	v_cmp_gt_u32_e32 vcc, 16, v208
	v_cndmask_b32_e64 v33, v210, v33, s[46:47]
	v_fmamk_f32 v34, v192, 0x3fb8aa3b, v34
	v_add_u32_e32 v211, 3, v189
	v_cmp_gt_u32_e64 s[46:47], 16, v211
	v_cndmask_b32_e32 v34, v210, v34, vcc
	v_fmamk_f32 v35, v193, 0x3fb8aa3b, v35
	v_add_u32_e32 v208, 8, v189
	v_cmp_gt_u32_e32 vcc, 16, v208
	v_cndmask_b32_e64 v35, v210, v35, s[46:47]
	v_fmamk_f32 v36, v194, 0x3fb8aa3b, v36
	v_add_u32_e32 v211, 9, v189
	v_cmp_gt_u32_e64 s[46:47], 16, v211
	v_cndmask_b32_e32 v36, v210, v36, vcc
	v_fmamk_f32 v37, v195, 0x3fb8aa3b, v37
	v_add_u32_e32 v208, 10, v189
	v_cmp_gt_u32_e32 vcc, 16, v208
	v_cndmask_b32_e64 v37, v210, v37, s[46:47]
	v_fmamk_f32 v38, v196, 0x3fb8aa3b, v38
	v_add_u32_e32 v211, 11, v189
	v_cmp_gt_u32_e64 s[46:47], 16, v211
	v_cndmask_b32_e32 v38, v210, v38, vcc
	v_fmamk_f32 v39, v197, 0x3fb8aa3b, v39
	v_add_u32_e32 v208, 16, v189
	v_cmp_gt_u32_e32 vcc, 16, v208
	v_cndmask_b32_e64 v39, v210, v39, s[46:47]
	v_fmamk_f32 v40, v198, 0x3fb8aa3b, v40
	v_add_u32_e32 v211, 17, v189
	v_cmp_gt_u32_e64 s[46:47], 16, v211
	v_cndmask_b32_e32 v40, v210, v40, vcc
	v_fmamk_f32 v41, v199, 0x3fb8aa3b, v41
	v_add_u32_e32 v208, 18, v189
	v_cmp_gt_u32_e32 vcc, 16, v208
	v_cndmask_b32_e64 v41, v210, v41, s[46:47]
	v_fmamk_f32 v42, v200, 0x3fb8aa3b, v42
	v_add_u32_e32 v211, 19, v189
	v_cmp_gt_u32_e64 s[46:47], 16, v211
	v_cndmask_b32_e32 v42, v210, v42, vcc
	v_fmamk_f32 v43, v201, 0x3fb8aa3b, v43
	v_add_u32_e32 v208, 24, v189
	v_cmp_gt_u32_e32 vcc, 16, v208
	v_cndmask_b32_e64 v43, v210, v43, s[46:47]
	v_fmamk_f32 v44, v202, 0x3fb8aa3b, v44
	v_add_u32_e32 v211, 25, v189
	v_cmp_gt_u32_e64 s[46:47], 16, v211
	v_cndmask_b32_e32 v44, v210, v44, vcc
	v_fmamk_f32 v45, v203, 0x3fb8aa3b, v45
	v_add_u32_e32 v208, 26, v189
	v_cmp_gt_u32_e32 vcc, 16, v208
	v_cndmask_b32_e64 v45, v210, v45, s[46:47]
	v_fmamk_f32 v46, v204, 0x3fb8aa3b, v46
	v_add_u32_e32 v211, 27, v189
	v_cmp_gt_u32_e64 s[46:47], 16, v211
	v_cndmask_b32_e32 v46, v210, v46, vcc
	v_fmamk_f32 v47, v205, 0x3fb8aa3b, v47
	s_nop 0
	v_cndmask_b32_e64 v47, v210, v47, s[46:47]
	s_branch .LBB0_392
